# attention loop: one LDS wait per two PV MFMAs, pack-before-sum flush removes the hazard s_nops (10 fewer instructions per tile)
# speedup vs baseline: 1.0136x; 1.0002x over previous
; __device__ __forceinline__ void exp_half(f32x16& p) {
; #pragma unroll
;     for (int r = 0; r < 16; ++r) p[r] = __builtin_amdgcn_exp2f(p[r]);
; }
; __device__ __forceinline__ void pack_p(const f32x16& p0, const f32x16& p1, float& l_reg, bf16x8& pa0, bf16x8& pa1, bf16x8& pa2, bf16x8& pa3) {
;     float ps = 0;
; #pragma unroll
;     for (int r = 0; r < 16; ++r) ps += p0[r];
; #pragma unroll
;     for (int r = 0; r < 16; ++r) ps += p1[r];
;     l_reg += ps;
;     ...
;     PK4(p0, 0, pa0); PK4(p0, 8, pa1); PK4(p1, 0, pa2); PK4(p1, 8, pa3);
;     ...
; }
; __device__ __forceinline__ void diff_unit(const DiffArgs& A, int b, int h, int qb, char* lds, int wv) {
;     ...
;     float l_reg = 0; f32x16 o[4] = {}; bf16x8 qr[4];
;     { const char* Qw = Pb + (size_t)(qb * 128 + wq * 32) * (INC * 2) + (C_DQ + c * 64) * 2; const unsigned qoff = (unsigned)((r32 * INC + hi * 8) * 2);
; #pragma unroll
;       for (int d0 = 0; d0 < 4; ++d0) qr[d0] = *reinterpret_cast<const bf16x8*>(Qw + qoff + d0 * 32); }
;     const int colB0 = c * 128;
;     const int krow = wid * 4 + (lane >> 4), kcc = (lane & 15) ^ (krow & 15);
;     const unsigned koff = (unsigned)((krow * INC + kcc * 8) * 2);
;     const int vkey = (wid >> 2) * 16 + (((wid >> 1) & 1) << 3) + (((lane >> 4) & 1) << 2) + ((lane >> 2) & 3)  , vcol = ((wid & 1) * 2 + (lane >> 5)) * 32 + (lane & 3) * 8;
;     const unsigned voff = (unsigned)((vkey * INC + vcol) * 2 + (C_DV - C_DK) * 2);
;     const int vb0 = (int)(uintptr_t)V_lds + v_rd_base(lane);
;     const char* Pk = Pb + (size_t)(t_lo * KVBLK) * (INC * 2) + C_DK * 2; int iposk = ipos - t_lo * KVBLK - 4 * hi; asm volatile("" : "+v"(iposk));     const int relw = t_lo * KVBLK - (qb * 128 + wq * 32);
;     typedef __attribute__((address_space(3))) unsigned lds_u32;
;     __attribute__((address_space(3))) unsigned char* ldsA = (__attribute__((address_space(3))) unsigned char*)lds + wid * 1024;
;     ...
;     f32x16 pA0, pA1, pB0, pB1; bf16x8 pa0, pa1, pa2, pa3; const int NT = nt;
;     STAGE(0); ENDI();
;     STAGE(1);
;     BIAS(pA0, pA1, 0); qkt<4>(pA0, pA1, K_lds, qr, r32, hi, colB0);
;     ...
;     if (c == 0) {
;     ...
;         const int lp_ = opaque_tid(wv) & 63, r32p = lp_ & 31, hip = lp_ >> 5;
;         exp_half(pA0);
;         ENDI();
; #pragma unroll 1
;         for (int j = 1; j + 1 < NT; j += 2) {
;             STAGE(j + 1);
.Lsym_entry:
	v_mov_b32_e32 v0, 0
	v_mov_b32_e32 v1, 0
	v_mov_b32_e32 v2, 0
	v_mov_b32_e32 v3, 0
	v_mov_b32_e32 v4, 0
	v_mov_b32_e32 v5, 0
	v_mov_b32_e32 v6, 0
	v_mov_b32_e32 v7, 0
	v_mov_b32_e32 v8, 0
	v_mov_b32_e32 v9, 0
	v_mov_b32_e32 v10, 0
	v_mov_b32_e32 v11, 0
	v_mov_b32_e32 v12, 0
	v_mov_b32_e32 v13, 0
	v_mov_b32_e32 v14, 0
	v_mov_b32_e32 v15, 0
	v_mov_b32_e32 v16, 0
	v_mov_b32_e32 v17, 0
	v_mov_b32_e32 v18, 0
	v_mov_b32_e32 v19, 0
	v_mov_b32_e32 v20, 0
	v_mov_b32_e32 v21, 0
	v_mov_b32_e32 v22, 0
	v_mov_b32_e32 v23, 0
	v_mov_b32_e32 v24, 0
	v_mov_b32_e32 v25, 0
	v_mov_b32_e32 v26, 0
	v_mov_b32_e32 v27, 0
	v_mov_b32_e32 v28, 0
	v_mov_b32_e32 v29, 0
	v_mov_b32_e32 v30, 0
	v_mov_b32_e32 v31, 0
	v_mov_b32_e32 v32, 0
	v_mov_b32_e32 v33, 0
	v_mov_b32_e32 v34, 0
	v_mov_b32_e32 v35, 0
	v_mov_b32_e32 v36, 0
	v_mov_b32_e32 v37, 0
	v_mov_b32_e32 v38, 0
	v_mov_b32_e32 v39, 0
	v_mov_b32_e32 v40, 0
	v_mov_b32_e32 v41, 0
	v_mov_b32_e32 v42, 0
	v_mov_b32_e32 v43, 0
	v_mov_b32_e32 v44, 0
	v_mov_b32_e32 v45, 0
	v_mov_b32_e32 v46, 0
	v_mov_b32_e32 v47, 0
	v_mov_b32_e32 v48, 0
	v_mov_b32_e32 v49, 0
	v_mov_b32_e32 v50, 0
	v_mov_b32_e32 v51, 0
	v_mov_b32_e32 v52, 0
	v_mov_b32_e32 v53, 0
	v_mov_b32_e32 v54, 0
	v_mov_b32_e32 v55, 0
	v_mov_b32_e32 v56, 0
	v_mov_b32_e32 v57, 0
	v_mov_b32_e32 v58, 0
	v_mov_b32_e32 v59, 0
	v_mov_b32_e32 v60, 0
	v_mov_b32_e32 v61, 0
	v_mov_b32_e32 v62, 0
	v_mov_b32_e32 v63, 0
	v_mov_b32_e32 v182, 0
	v_mbcnt_lo_u32_b32 v190, -1, 0
	v_mbcnt_hi_u32_b32 v190, -1, v190
	v_and_b32_e32 v191, 31, v190
	v_lshrrev_b32_e32 v187, 5, v190
	v_lshlrev_b32_e32 v185, 4, v187
	v_or_b32_e32 v185, s52, v185
	v_and_b32_e32 v183, 15, v191
	v_lshlrev_b32_e32 v183, 4, v183
	v_xor_b32_e32 v185, v185, v183
	v_lshlrev_b32_e32 v183, 8, v191
	v_xor_b32_e32 v178, 0, v185
	v_add_u32_e32 v178, v178, v183
	v_add_u32_e32 v178, 0x10000, v178
	v_xor_b32_e32 v179, 32, v185
	v_add_u32_e32 v179, v179, v183
	v_add_u32_e32 v179, 0x10000, v179
	v_xor_b32_e32 v180, 64, v185
	v_add_u32_e32 v180, v180, v183
	v_add_u32_e32 v180, 0x10000, v180
	v_xor_b32_e32 v181, 96, v185
	v_add_u32_e32 v181, v181, v183
	v_add_u32_e32 v181, 0x10000, v181
	s_add_i32 s55, s63, 64
	v_subrev_u32_e32 v183, 64, v236
	v_cvt_f32_i32_e32 v183, v183
	s_mov_b32 s54, 0
	s_add_u32 s56, s20, 0x1c1e00
	s_addc_u32 s57, s21, 0
	v_exp_f32_e32 v80, v80
	v_exp_f32_e32 v81, v81
	v_exp_f32_e32 v82, v82
	v_exp_f32_e32 v83, v83
	v_add_f32_e32 v182, v80, v182
	v_add_f32_e32 v182, v81, v182
	v_cvt_pk_bf16_f32 v128, v80, v81
	v_exp_f32_e32 v84, v84
	v_exp_f32_e32 v85, v85
	v_add_f32_e32 v182, v82, v182
	v_add_f32_e32 v182, v83, v182
	v_cvt_pk_bf16_f32 v129, v82, v83
	v_exp_f32_e32 v86, v86
	v_exp_f32_e32 v87, v87
	v_add_f32_e32 v182, v84, v182
	v_add_f32_e32 v182, v85, v182
	v_cvt_pk_bf16_f32 v130, v84, v85
	v_cvt_pk_bf16_f32 v131, v86, v87
	v_add_f32_e32 v182, v86, v182
	v_add_f32_e32 v182, v87, v182

; template <int KS> __device__ __forceinline__ void pv_ks(f32x16* o, int vb, bf16x8 pa) {
;     const s16x4 l0 = tr_read<v_rd_off(0, KS, 0)>(vb), h0 = tr_read<v_rd_off(0, KS, 1)>(vb), l1 = tr_read<v_rd_off(1, KS, 0)>(vb), h1 = tr_read<v_rd_off(1, KS, 1)>(vb);
;     const s16x4 l2 = tr_read<v_rd_off(2, KS, 0)>(vb), h2 = tr_read<v_rd_off(2, KS, 1)>(vb), l3 = tr_read<v_rd_off(3, KS, 0)>(vb), h3 = tr_read<v_rd_off(3, KS, 1)>(vb);
;     ...
;     asm volatile("s_waitcnt lgkmcnt(6)" ::: "memory"); SBAR();
;     o[0] = __builtin_amdgcn_mfma_f32_32x32x16_bf16(pa, PK(l0, h0), o[0], 0, 0, 0);
;     asm volatile("s_waitcnt lgkmcnt(4)" ::: "memory"); SBAR();
;     o[1] = __builtin_amdgcn_mfma_f32_32x32x16_bf16(pa, PK(l1, h1), o[1], 0, 0, 0);
;     asm volatile("s_waitcnt lgkmcnt(2)" ::: "memory"); SBAR();
;     o[2] = __builtin_amdgcn_mfma_f32_32x32x16_bf16(pa, PK(l2, h2), o[2], 0, 0, 0);
;     asm volatile("s_waitcnt lgkmcnt(0)" ::: "memory"); SBAR();
;     o[3] = __builtin_amdgcn_mfma_f32_32x32x16_bf16(pa, PK(l3, h3), o[3], 0, 0, 0);
;     ...
; }
; __device__ __forceinline__ void pv_d0(f32x16* o, int vb, bf16x8 pa0, bf16x8 pa1, bf16x8 pa2, bf16x8 pa3) {
;     __builtin_amdgcn_s_setprio(1);
;     pv_ks<0>(o, vb, pa0); pv_ks<1>(o, vb, pa1); pv_ks<2>(o, vb, pa2); pv_ks<3>(o, vb, pa3);
;     __builtin_amdgcn_s_setprio(0);
; }
; __device__ __forceinline__ void exp_half(f32x16& p) {
; #pragma unroll
;     for (int r = 0; r < 16; ++r) p[r] = __builtin_amdgcn_exp2f(p[r]);
; }
; __device__ __forceinline__ void pack_p(const f32x16& p0, const f32x16& p1, float& l_reg, bf16x8& pa0, bf16x8& pa1, bf16x8& pa2, bf16x8& pa3) {
;     float ps = 0;
; #pragma unroll
;     for (int r = 0; r < 16; ++r) ps += p0[r];
; #pragma unroll
;     for (int r = 0; r < 16; ++r) ps += p1[r];
;     l_reg += ps;
;     ...
;     PK4(p0, 0, pa0); PK4(p0, 8, pa1); PK4(p1, 0, pa2); PK4(p1, 8, pa3);
;     ...
; }
; template <int ND0> __device__ __forceinline__ void qkt(f32x16& p0, f32x16& p1, const char* Ks, const bf16x8* qr, int r32, int hi, int colB0) {
; #pragma unroll
;     for (int d0 = 0; d0 < ND0; ++d0) { const int cb = colB0 + (d0 * 16 + hi * 8) * 2;
;         const bf16x8 b0 = *reinterpret_cast<const bf16x8*>(Ks + KSWZ(r32, cb));
;         const bf16x8 b1 = *reinterpret_cast<const bf16x8*>(Ks + KSWZ(32 + r32, cb));
;         p0 = __builtin_amdgcn_mfma_f32_32x32x16_bf16(b0, qr[d0], p0, 0, 0, 0);
.Lsym_biasdone_s0:
	s_add_i32 s55, s55, 64
	v_add_f32_e32 v183, 0xc2800000, v183
	ds_read_b64_tr_b16 v[144:145], v252 offset:0
	ds_read_b64_tr_b16 v[146:147], v252 offset:2048
	ds_read_b64_tr_b16 v[148:149], v252 offset:512
	ds_read_b64_tr_b16 v[150:151], v252 offset:2560
	ds_read_b64_tr_b16 v[152:153], v252 offset:1024
	ds_read_b64_tr_b16 v[154:155], v252 offset:3072
	ds_read_b64_tr_b16 v[156:157], v252 offset:1536
	ds_read_b64_tr_b16 v[158:159], v252 offset:3584
	s_waitcnt lgkmcnt(4)
	v_mfma_f32_32x32x16_bf16 v[48:63], v[128:131], v[144:147], v[48:63]
	ds_read_b64_tr_b16 v[144:145], v252 offset:4096
	ds_read_b64_tr_b16 v[146:147], v252 offset:6144
	v_exp_f32_e32 v88, v88
	v_exp_f32_e32 v89, v89
	v_mfma_f32_32x32x16_bf16 v[32:47], v[128:131], v[148:151], v[32:47]
	ds_read_b64_tr_b16 v[148:149], v252 offset:4608
	ds_read_b64_tr_b16 v[150:151], v252 offset:6656
	v_exp_f32_e32 v90, v90
	v_exp_f32_e32 v91, v91
	v_add_f32_e32 v182, v88, v182
	v_add_f32_e32 v182, v89, v182
	v_cvt_pk_bf16_f32 v132, v88, v89
	s_waitcnt lgkmcnt(4)
	v_mfma_f32_32x32x16_bf16 v[16:31], v[128:131], v[152:155], v[16:31]
	ds_read_b64_tr_b16 v[152:153], v252 offset:5120
	ds_read_b64_tr_b16 v[154:155], v252 offset:7168
	v_exp_f32_e32 v92, v92
	v_exp_f32_e32 v93, v93
	v_add_f32_e32 v182, v90, v182
	v_add_f32_e32 v182, v91, v182
	v_cvt_pk_bf16_f32 v133, v90, v91
	v_mfma_f32_32x32x16_bf16 v[0:15], v[128:131], v[156:159], v[0:15]
	ds_read_b64_tr_b16 v[156:157], v252 offset:5632
	ds_read_b64_tr_b16 v[158:159], v252 offset:7680
	v_exp_f32_e32 v94, v94
	v_exp_f32_e32 v95, v95
	v_add_f32_e32 v182, v92, v182
	v_add_f32_e32 v182, v93, v182
	v_cvt_pk_bf16_f32 v134, v92, v93
	v_cvt_pk_bf16_f32 v135, v94, v95
	v_add_f32_e32 v182, v94, v182
	v_add_f32_e32 v182, v95, v182
	v_mfma_f32_32x32x16_bf16 v[112:127], v[192:195], v[172:175], v[112:127]
	v_mfma_f32_32x32x16_bf16 v[96:111], v[196:199], v[172:175], v[96:111]
	v_mfma_f32_32x32x16_bf16 v[112:127], v[200:203], v[168:171], v[112:127]
	v_mfma_f32_32x32x16_bf16 v[96:111], v[204:207], v[168:171], v[96:111]
	s_waitcnt lgkmcnt(4)
	v_mfma_f32_32x32x16_bf16 v[48:63], v[132:135], v[144:147], v[48:63]
	ds_read_b64_tr_b16 v[144:145], v252 offset:8192
	ds_read_b64_tr_b16 v[146:147], v252 offset:10240
	v_exp_f32_e32 v64, v64
	v_exp_f32_e32 v65, v65
	v_mfma_f32_32x32x16_bf16 v[32:47], v[132:135], v[148:151], v[32:47]
	ds_read_b64_tr_b16 v[148:149], v252 offset:8704
	ds_read_b64_tr_b16 v[150:151], v252 offset:10752
	v_exp_f32_e32 v66, v66
	v_exp_f32_e32 v67, v67
	v_add_f32_e32 v182, v64, v182
	v_add_f32_e32 v182, v65, v182
	v_cvt_pk_bf16_f32 v136, v64, v65
	s_waitcnt lgkmcnt(4)
	v_mfma_f32_32x32x16_bf16 v[16:31], v[132:135], v[152:155], v[16:31]
	ds_read_b64_tr_b16 v[152:153], v252 offset:9216
	ds_read_b64_tr_b16 v[154:155], v252 offset:11264
	v_exp_f32_e32 v68, v68
	v_exp_f32_e32 v69, v69
	v_add_f32_e32 v182, v66, v182
	v_add_f32_e32 v182, v67, v182
	v_cvt_pk_bf16_f32 v137, v66, v67
	v_mfma_f32_32x32x16_bf16 v[0:15], v[132:135], v[156:159], v[0:15]
	ds_read_b64_tr_b16 v[156:157], v252 offset:9728
	ds_read_b64_tr_b16 v[158:159], v252 offset:11776
	v_exp_f32_e32 v70, v70
	v_exp_f32_e32 v71, v71
	v_add_f32_e32 v182, v68, v182
	v_add_f32_e32 v182, v69, v182
	v_cvt_pk_bf16_f32 v138, v68, v69
	v_cvt_pk_bf16_f32 v139, v70, v71
	v_add_f32_e32 v182, v70, v182
	v_add_f32_e32 v182, v71, v182
	v_mfma_f32_32x32x16_bf16 v[112:127], v[208:211], v[164:167], v[112:127]
	v_mfma_f32_32x32x16_bf16 v[96:111], v[212:215], v[164:167], v[96:111]
	v_mfma_f32_32x32x16_bf16 v[112:127], v[216:219], v[160:163], v[112:127]
	v_mfma_f32_32x32x16_bf16 v[96:111], v[220:223], v[160:163], v[96:111]
	s_waitcnt lgkmcnt(4)
	v_mfma_f32_32x32x16_bf16 v[48:63], v[136:139], v[144:147], v[48:63]
	ds_read_b64_tr_b16 v[144:145], v252 offset:12288
	ds_read_b64_tr_b16 v[146:147], v252 offset:14336
	v_exp_f32_e32 v72, v72
	v_exp_f32_e32 v73, v73
	v_mfma_f32_32x32x16_bf16 v[32:47], v[136:139], v[148:151], v[32:47]
	ds_read_b64_tr_b16 v[148:149], v252 offset:12800
	ds_read_b64_tr_b16 v[150:151], v252 offset:14848
	v_exp_f32_e32 v74, v74
	v_exp_f32_e32 v75, v75
	v_add_f32_e32 v182, v72, v182
	v_add_f32_e32 v182, v73, v182
	v_cvt_pk_bf16_f32 v140, v72, v73
	s_waitcnt lgkmcnt(4)
	v_mfma_f32_32x32x16_bf16 v[16:31], v[136:139], v[152:155], v[16:31]
	ds_read_b64_tr_b16 v[152:153], v252 offset:13312
	ds_read_b64_tr_b16 v[154:155], v252 offset:15360
	v_exp_f32_e32 v76, v76
	v_exp_f32_e32 v77, v77
	v_add_f32_e32 v182, v74, v182
	v_add_f32_e32 v182, v75, v182
	v_cvt_pk_bf16_f32 v141, v74, v75
	v_mfma_f32_32x32x16_bf16 v[0:15], v[136:139], v[156:159], v[0:15]
	ds_read_b64_tr_b16 v[156:157], v252 offset:13824
	ds_read_b64_tr_b16 v[158:159], v252 offset:15872
	v_exp_f32_e32 v78, v78
	v_exp_f32_e32 v79, v79
	v_add_f32_e32 v182, v76, v182
	v_add_f32_e32 v182, v77, v182
	v_cvt_pk_bf16_f32 v142, v76, v77
	v_cvt_pk_bf16_f32 v143, v78, v79
	v_add_f32_e32 v182, v78, v182
	v_add_f32_e32 v182, v79, v182
	s_waitcnt lgkmcnt(4)
	v_mfma_f32_32x32x16_bf16 v[48:63], v[140:143], v[144:147], v[48:63]
	v_exp_f32_e32 v112, v112
	v_exp_f32_e32 v113, v113
	v_mfma_f32_32x32x16_bf16 v[32:47], v[140:143], v[148:151], v[32:47]
	v_exp_f32_e32 v114, v114
	v_exp_f32_e32 v115, v115
	v_add_f32_e32 v182, v112, v182
	v_add_f32_e32 v182, v113, v182
	v_cvt_pk_bf16_f32 v128, v112, v113
	s_waitcnt lgkmcnt(0)
	v_mfma_f32_32x32x16_bf16 v[16:31], v[140:143], v[152:155], v[16:31]
	v_exp_f32_e32 v116, v116
	v_exp_f32_e32 v117, v117
	v_add_f32_e32 v182, v114, v182
	v_add_f32_e32 v182, v115, v182
	v_cvt_pk_bf16_f32 v129, v114, v115
	v_mfma_f32_32x32x16_bf16 v[0:15], v[140:143], v[156:159], v[0:15]
	v_exp_f32_e32 v118, v118
	v_exp_f32_e32 v119, v119
	v_add_f32_e32 v182, v116, v182
	v_add_f32_e32 v182, v117, v182
	v_cvt_pk_bf16_f32 v130, v116, v117
	v_cvt_pk_bf16_f32 v131, v118, v119
	v_add_f32_e32 v182, v118, v182
	v_add_f32_e32 v182, v119, v182
	s_add_i32 s54, s54, 1
	s_cmp_ge_i32 s54, s62
	s_cbranch_scc1 .Lsym_last1
	s_waitcnt vmcnt(0)
	s_barrier
	ds_read_b128 v[192:195], v178 offset:32768
	ds_read_b128 v[196:199], v178 offset:40960
	ds_read_b128 v[200:203], v179 offset:32768
	ds_read_b128 v[204:207], v179 offset:40960
	ds_read_b128 v[208:211], v180 offset:32768
	ds_read_b128 v[212:215], v180 offset:40960
	ds_read_b128 v[216:219], v181 offset:32768
	ds_read_b128 v[220:223], v181 offset:40960
	s_add_i32 s53, s54, 2
	s_cmp_le_i32 s53, s62
	s_cbranch_scc0 .Lsym_nostage_s1
	s_add_i32 m0, s25, 0xc000
	s_add_u32 s60, s56, 0x70000
	s_addc_u32 s61, s57, 0
	global_load_lds_dwordx4 v176, s[56:57]
	s_add_i32 m0, s24, 0xc000
	s_nop 0
	global_load_lds_dwordx4 v188, s[56:57]
	s_add_i32 m0, s25, 0xe000
	s_add_u32 s56, s56, 0xe0000
	s_addc_u32 s57, s57, 0
	global_load_lds_dwordx4 v176, s[60:61]
	s_add_i32 m0, s24, 0xe000
	s_nop 0
	global_load_lds_dwordx4 v188, s[60:61]

; template <int KS> __device__ __forceinline__ void pv_ks(f32x16* o, int vb, bf16x8 pa) {
;     const s16x4 l0 = tr_read<v_rd_off(0, KS, 0)>(vb), h0 = tr_read<v_rd_off(0, KS, 1)>(vb), l1 = tr_read<v_rd_off(1, KS, 0)>(vb), h1 = tr_read<v_rd_off(1, KS, 1)>(vb);
;     const s16x4 l2 = tr_read<v_rd_off(2, KS, 0)>(vb), h2 = tr_read<v_rd_off(2, KS, 1)>(vb), l3 = tr_read<v_rd_off(3, KS, 0)>(vb), h3 = tr_read<v_rd_off(3, KS, 1)>(vb);
;     ...
;     asm volatile("s_waitcnt lgkmcnt(6)" ::: "memory"); SBAR();
;     o[0] = __builtin_amdgcn_mfma_f32_32x32x16_bf16(pa, PK(l0, h0), o[0], 0, 0, 0);
;     asm volatile("s_waitcnt lgkmcnt(4)" ::: "memory"); SBAR();
;     o[1] = __builtin_amdgcn_mfma_f32_32x32x16_bf16(pa, PK(l1, h1), o[1], 0, 0, 0);
;     asm volatile("s_waitcnt lgkmcnt(2)" ::: "memory"); SBAR();
;     o[2] = __builtin_amdgcn_mfma_f32_32x32x16_bf16(pa, PK(l2, h2), o[2], 0, 0, 0);
;     asm volatile("s_waitcnt lgkmcnt(0)" ::: "memory"); SBAR();
;     o[3] = __builtin_amdgcn_mfma_f32_32x32x16_bf16(pa, PK(l3, h3), o[3], 0, 0, 0);
;     ...
; }
; __device__ __forceinline__ void pv_d0(f32x16* o, int vb, bf16x8 pa0, bf16x8 pa1, bf16x8 pa2, bf16x8 pa3) {
;     __builtin_amdgcn_s_setprio(1);
;     pv_ks<0>(o, vb, pa0); pv_ks<1>(o, vb, pa1); pv_ks<2>(o, vb, pa2); pv_ks<3>(o, vb, pa3);
;     __builtin_amdgcn_s_setprio(0);
; }
; __device__ __forceinline__ void exp_half(f32x16& p) {
; #pragma unroll
;     for (int r = 0; r < 16; ++r) p[r] = __builtin_amdgcn_exp2f(p[r]);
; }
; __device__ __forceinline__ void pack_p(const f32x16& p0, const f32x16& p1, float& l_reg, bf16x8& pa0, bf16x8& pa1, bf16x8& pa2, bf16x8& pa3) {
;     float ps = 0;
; #pragma unroll
;     for (int r = 0; r < 16; ++r) ps += p0[r];
; #pragma unroll
;     for (int r = 0; r < 16; ++r) ps += p1[r];
;     l_reg += ps;
;     ...
;     PK4(p0, 0, pa0); PK4(p0, 8, pa1); PK4(p1, 0, pa2); PK4(p1, 8, pa3);
;     ...
; }
; template <int ND0> __device__ __forceinline__ void qkt(f32x16& p0, f32x16& p1, const char* Ks, const bf16x8* qr, int r32, int hi, int colB0) {
; #pragma unroll
;     for (int d0 = 0; d0 < ND0; ++d0) { const int cb = colB0 + (d0 * 16 + hi * 8) * 2;
;         const bf16x8 b0 = *reinterpret_cast<const bf16x8*>(Ks + KSWZ(r32, cb));
;         const bf16x8 b1 = *reinterpret_cast<const bf16x8*>(Ks + KSWZ(32 + r32, cb));
;         p0 = __builtin_amdgcn_mfma_f32_32x32x16_bf16(b0, qr[d0], p0, 0, 0, 0);
.Lsym_biasdone_s1:
	s_add_i32 s55, s55, 64
	v_add_f32_e32 v183, 0xc2800000, v183
	ds_read_b64_tr_b16 v[144:145], v252 offset:16384
	ds_read_b64_tr_b16 v[146:147], v252 offset:18432
	ds_read_b64_tr_b16 v[148:149], v252 offset:16896
	ds_read_b64_tr_b16 v[150:151], v252 offset:18944
	ds_read_b64_tr_b16 v[152:153], v252 offset:17408
	ds_read_b64_tr_b16 v[154:155], v252 offset:19456
	ds_read_b64_tr_b16 v[156:157], v252 offset:17920
	ds_read_b64_tr_b16 v[158:159], v252 offset:19968
	s_waitcnt lgkmcnt(4)
	v_mfma_f32_32x32x16_bf16 v[48:63], v[128:131], v[144:147], v[48:63]
	ds_read_b64_tr_b16 v[144:145], v252 offset:20480
	ds_read_b64_tr_b16 v[146:147], v252 offset:22528
	v_exp_f32_e32 v120, v120
	v_exp_f32_e32 v121, v121
	v_mfma_f32_32x32x16_bf16 v[32:47], v[128:131], v[148:151], v[32:47]
	ds_read_b64_tr_b16 v[148:149], v252 offset:20992
	ds_read_b64_tr_b16 v[150:151], v252 offset:23040
	v_exp_f32_e32 v122, v122
	v_exp_f32_e32 v123, v123
	v_add_f32_e32 v182, v120, v182
	v_add_f32_e32 v182, v121, v182
	v_cvt_pk_bf16_f32 v132, v120, v121
	s_waitcnt lgkmcnt(4)
	v_mfma_f32_32x32x16_bf16 v[16:31], v[128:131], v[152:155], v[16:31]
	ds_read_b64_tr_b16 v[152:153], v252 offset:21504
	ds_read_b64_tr_b16 v[154:155], v252 offset:23552
	v_exp_f32_e32 v124, v124
	v_exp_f32_e32 v125, v125
	v_add_f32_e32 v182, v122, v182
	v_add_f32_e32 v182, v123, v182
	v_cvt_pk_bf16_f32 v133, v122, v123
	v_mfma_f32_32x32x16_bf16 v[0:15], v[128:131], v[156:159], v[0:15]
	ds_read_b64_tr_b16 v[156:157], v252 offset:22016
	ds_read_b64_tr_b16 v[158:159], v252 offset:24064
	v_exp_f32_e32 v126, v126
	v_exp_f32_e32 v127, v127
	v_add_f32_e32 v182, v124, v182
	v_add_f32_e32 v182, v125, v182
	v_cvt_pk_bf16_f32 v134, v124, v125
	v_cvt_pk_bf16_f32 v135, v126, v127
	v_add_f32_e32 v182, v126, v182
	v_add_f32_e32 v182, v127, v182
	v_mfma_f32_32x32x16_bf16 v[80:95], v[192:195], v[172:175], v[80:95]
	v_mfma_f32_32x32x16_bf16 v[64:79], v[196:199], v[172:175], v[64:79]
	v_mfma_f32_32x32x16_bf16 v[80:95], v[200:203], v[168:171], v[80:95]
	v_mfma_f32_32x32x16_bf16 v[64:79], v[204:207], v[168:171], v[64:79]
	s_waitcnt lgkmcnt(4)
	v_mfma_f32_32x32x16_bf16 v[48:63], v[132:135], v[144:147], v[48:63]
	ds_read_b64_tr_b16 v[144:145], v252 offset:24576
	ds_read_b64_tr_b16 v[146:147], v252 offset:26624
	v_exp_f32_e32 v96, v96
	v_exp_f32_e32 v97, v97
	v_mfma_f32_32x32x16_bf16 v[32:47], v[132:135], v[148:151], v[32:47]
	ds_read_b64_tr_b16 v[148:149], v252 offset:25088
	ds_read_b64_tr_b16 v[150:151], v252 offset:27136
	v_exp_f32_e32 v98, v98
	v_exp_f32_e32 v99, v99
	v_add_f32_e32 v182, v96, v182
	v_add_f32_e32 v182, v97, v182
	v_cvt_pk_bf16_f32 v136, v96, v97
	s_waitcnt lgkmcnt(4)
	v_mfma_f32_32x32x16_bf16 v[16:31], v[132:135], v[152:155], v[16:31]
	ds_read_b64_tr_b16 v[152:153], v252 offset:25600
	ds_read_b64_tr_b16 v[154:155], v252 offset:27648
	v_exp_f32_e32 v100, v100
	v_exp_f32_e32 v101, v101
	v_add_f32_e32 v182, v98, v182
	v_add_f32_e32 v182, v99, v182
	v_cvt_pk_bf16_f32 v137, v98, v99
	v_mfma_f32_32x32x16_bf16 v[0:15], v[132:135], v[156:159], v[0:15]
	ds_read_b64_tr_b16 v[156:157], v252 offset:26112
	ds_read_b64_tr_b16 v[158:159], v252 offset:28160
	v_exp_f32_e32 v102, v102
	v_exp_f32_e32 v103, v103
	v_add_f32_e32 v182, v100, v182
	v_add_f32_e32 v182, v101, v182
	v_cvt_pk_bf16_f32 v138, v100, v101
	v_cvt_pk_bf16_f32 v139, v102, v103
	v_add_f32_e32 v182, v102, v182
	v_add_f32_e32 v182, v103, v182
	v_mfma_f32_32x32x16_bf16 v[80:95], v[208:211], v[164:167], v[80:95]
	v_mfma_f32_32x32x16_bf16 v[64:79], v[212:215], v[164:167], v[64:79]
	v_mfma_f32_32x32x16_bf16 v[80:95], v[216:219], v[160:163], v[80:95]
	v_mfma_f32_32x32x16_bf16 v[64:79], v[220:223], v[160:163], v[64:79]
	s_waitcnt lgkmcnt(4)
	v_mfma_f32_32x32x16_bf16 v[48:63], v[136:139], v[144:147], v[48:63]
	ds_read_b64_tr_b16 v[144:145], v252 offset:28672
	ds_read_b64_tr_b16 v[146:147], v252 offset:30720
	v_exp_f32_e32 v104, v104
	v_exp_f32_e32 v105, v105
	v_mfma_f32_32x32x16_bf16 v[32:47], v[136:139], v[148:151], v[32:47]
	ds_read_b64_tr_b16 v[148:149], v252 offset:29184
	ds_read_b64_tr_b16 v[150:151], v252 offset:31232
	v_exp_f32_e32 v106, v106
	v_exp_f32_e32 v107, v107
	v_add_f32_e32 v182, v104, v182
	v_add_f32_e32 v182, v105, v182
	v_cvt_pk_bf16_f32 v140, v104, v105
	s_waitcnt lgkmcnt(4)
	v_mfma_f32_32x32x16_bf16 v[16:31], v[136:139], v[152:155], v[16:31]
	ds_read_b64_tr_b16 v[152:153], v252 offset:29696
	ds_read_b64_tr_b16 v[154:155], v252 offset:31744
	v_exp_f32_e32 v108, v108
	v_exp_f32_e32 v109, v109
	v_add_f32_e32 v182, v106, v182
	v_add_f32_e32 v182, v107, v182
	v_cvt_pk_bf16_f32 v141, v106, v107
	v_mfma_f32_32x32x16_bf16 v[0:15], v[136:139], v[156:159], v[0:15]
	ds_read_b64_tr_b16 v[156:157], v252 offset:30208
	ds_read_b64_tr_b16 v[158:159], v252 offset:32256
	v_exp_f32_e32 v110, v110
	v_exp_f32_e32 v111, v111
	v_add_f32_e32 v182, v108, v182
	v_add_f32_e32 v182, v109, v182
	v_cvt_pk_bf16_f32 v142, v108, v109
	v_cvt_pk_bf16_f32 v143, v110, v111
	v_add_f32_e32 v182, v110, v182
	v_add_f32_e32 v182, v111, v182
	s_waitcnt lgkmcnt(4)
	v_mfma_f32_32x32x16_bf16 v[48:63], v[140:143], v[144:147], v[48:63]
	v_exp_f32_e32 v80, v80
	v_exp_f32_e32 v81, v81
	v_mfma_f32_32x32x16_bf16 v[32:47], v[140:143], v[148:151], v[32:47]
	v_exp_f32_e32 v82, v82
	v_exp_f32_e32 v83, v83
	v_add_f32_e32 v182, v80, v182
	v_add_f32_e32 v182, v81, v182
	v_cvt_pk_bf16_f32 v128, v80, v81
	s_waitcnt lgkmcnt(0)
	v_mfma_f32_32x32x16_bf16 v[16:31], v[140:143], v[152:155], v[16:31]
	v_exp_f32_e32 v84, v84
	v_exp_f32_e32 v85, v85
	v_add_f32_e32 v182, v82, v182
	v_add_f32_e32 v182, v83, v182
	v_cvt_pk_bf16_f32 v129, v82, v83
	v_mfma_f32_32x32x16_bf16 v[0:15], v[140:143], v[156:159], v[0:15]
	v_exp_f32_e32 v86, v86
	v_exp_f32_e32 v87, v87
	v_add_f32_e32 v182, v84, v182
	v_add_f32_e32 v182, v85, v182
	v_cvt_pk_bf16_f32 v130, v84, v85
	v_cvt_pk_bf16_f32 v131, v86, v87
	v_add_f32_e32 v182, v86, v182
	v_add_f32_e32 v182, v87, v182
	s_add_i32 s54, s54, 1
	s_waitcnt vmcnt(0)
	s_barrier
	ds_read_b128 v[192:195], v178 offset:49152
	ds_read_b128 v[196:199], v178 offset:57344
	ds_read_b128 v[200:203], v179 offset:49152
	ds_read_b128 v[204:207], v179 offset:57344
	ds_read_b128 v[208:211], v180 offset:49152
	ds_read_b128 v[212:215], v180 offset:57344
	ds_read_b128 v[216:219], v181 offset:49152
	ds_read_b128 v[220:223], v181 offset:57344
	s_add_i32 s53, s54, 2
	s_cmp_le_i32 s53, s62
	s_cbranch_scc0 .Lsym_nostage_s2
	s_add_i32 m0, s25, 0x0
	s_add_u32 s60, s56, 0x70000
	s_addc_u32 s61, s57, 0
	global_load_lds_dwordx4 v176, s[56:57]
	s_add_i32 m0, s24, 0x0
	s_nop 0
	global_load_lds_dwordx4 v188, s[56:57]
	s_add_i32 m0, s25, 0x2000
	s_add_u32 s56, s56, 0xe0000
	s_addc_u32 s57, s57, 0
	global_load_lds_dwordx4 v176, s[60:61]
	s_add_i32 m0, s24, 0x2000
	s_nop 0
	global_load_lds_dwordx4 v188, s[60:61]

; template <int KS> __device__ __forceinline__ void pv_ks(f32x16* o, int vb, bf16x8 pa) {
;     const s16x4 l0 = tr_read<v_rd_off(0, KS, 0)>(vb), h0 = tr_read<v_rd_off(0, KS, 1)>(vb), l1 = tr_read<v_rd_off(1, KS, 0)>(vb), h1 = tr_read<v_rd_off(1, KS, 1)>(vb);
;     const s16x4 l2 = tr_read<v_rd_off(2, KS, 0)>(vb), h2 = tr_read<v_rd_off(2, KS, 1)>(vb), l3 = tr_read<v_rd_off(3, KS, 0)>(vb), h3 = tr_read<v_rd_off(3, KS, 1)>(vb);
;     ...
;     asm volatile("s_waitcnt lgkmcnt(6)" ::: "memory"); SBAR();
;     o[0] = __builtin_amdgcn_mfma_f32_32x32x16_bf16(pa, PK(l0, h0), o[0], 0, 0, 0);
;     asm volatile("s_waitcnt lgkmcnt(4)" ::: "memory"); SBAR();
;     o[1] = __builtin_amdgcn_mfma_f32_32x32x16_bf16(pa, PK(l1, h1), o[1], 0, 0, 0);
;     asm volatile("s_waitcnt lgkmcnt(2)" ::: "memory"); SBAR();
;     o[2] = __builtin_amdgcn_mfma_f32_32x32x16_bf16(pa, PK(l2, h2), o[2], 0, 0, 0);
;     asm volatile("s_waitcnt lgkmcnt(0)" ::: "memory"); SBAR();
;     o[3] = __builtin_amdgcn_mfma_f32_32x32x16_bf16(pa, PK(l3, h3), o[3], 0, 0, 0);
;     ...
; }
; __device__ __forceinline__ void pv_d0(f32x16* o, int vb, bf16x8 pa0, bf16x8 pa1, bf16x8 pa2, bf16x8 pa3) {
;     __builtin_amdgcn_s_setprio(1);
;     pv_ks<0>(o, vb, pa0); pv_ks<1>(o, vb, pa1); pv_ks<2>(o, vb, pa2); pv_ks<3>(o, vb, pa3);
;     __builtin_amdgcn_s_setprio(0);
; }
; __device__ __forceinline__ void exp_half(f32x16& p) {
; #pragma unroll
;     for (int r = 0; r < 16; ++r) p[r] = __builtin_amdgcn_exp2f(p[r]);
; }
; __device__ __forceinline__ void pack_p(const f32x16& p0, const f32x16& p1, float& l_reg, bf16x8& pa0, bf16x8& pa1, bf16x8& pa2, bf16x8& pa3) {
;     float ps = 0;
; #pragma unroll
;     for (int r = 0; r < 16; ++r) ps += p0[r];
; #pragma unroll
;     for (int r = 0; r < 16; ++r) ps += p1[r];
;     l_reg += ps;
;     ...
;     PK4(p0, 0, pa0); PK4(p0, 8, pa1); PK4(p1, 0, pa2); PK4(p1, 8, pa3);
;     ...
; }
; template <int ND0> __device__ __forceinline__ void qkt(f32x16& p0, f32x16& p1, const char* Ks, const bf16x8* qr, int r32, int hi, int colB0) {
; #pragma unroll
;     for (int d0 = 0; d0 < ND0; ++d0) { const int cb = colB0 + (d0 * 16 + hi * 8) * 2;
;         const bf16x8 b0 = *reinterpret_cast<const bf16x8*>(Ks + KSWZ(r32, cb));
;         const bf16x8 b1 = *reinterpret_cast<const bf16x8*>(Ks + KSWZ(32 + r32, cb));
;         p0 = __builtin_amdgcn_mfma_f32_32x32x16_bf16(b0, qr[d0], p0, 0, 0, 0);
.Lsym_biasdone_s2:
	s_add_i32 s55, s55, 64
	v_add_f32_e32 v183, 0xc2800000, v183
	ds_read_b64_tr_b16 v[144:145], v252 offset:32768
	ds_read_b64_tr_b16 v[146:147], v252 offset:34816
	ds_read_b64_tr_b16 v[148:149], v252 offset:33280
	ds_read_b64_tr_b16 v[150:151], v252 offset:35328
	ds_read_b64_tr_b16 v[152:153], v252 offset:33792
	ds_read_b64_tr_b16 v[154:155], v252 offset:35840
	ds_read_b64_tr_b16 v[156:157], v252 offset:34304
	ds_read_b64_tr_b16 v[158:159], v252 offset:36352
	s_waitcnt lgkmcnt(4)
	v_mfma_f32_32x32x16_bf16 v[48:63], v[128:131], v[144:147], v[48:63]
	ds_read_b64_tr_b16 v[144:145], v252 offset:36864
	ds_read_b64_tr_b16 v[146:147], v252 offset:38912
	v_exp_f32_e32 v88, v88
	v_exp_f32_e32 v89, v89
	v_mfma_f32_32x32x16_bf16 v[32:47], v[128:131], v[148:151], v[32:47]
	ds_read_b64_tr_b16 v[148:149], v252 offset:37376
	ds_read_b64_tr_b16 v[150:151], v252 offset:39424
	v_exp_f32_e32 v90, v90
	v_exp_f32_e32 v91, v91
	v_add_f32_e32 v182, v88, v182
	v_add_f32_e32 v182, v89, v182
	v_cvt_pk_bf16_f32 v132, v88, v89
	s_waitcnt lgkmcnt(4)
	v_mfma_f32_32x32x16_bf16 v[16:31], v[128:131], v[152:155], v[16:31]
	ds_read_b64_tr_b16 v[152:153], v252 offset:37888
	ds_read_b64_tr_b16 v[154:155], v252 offset:39936
	v_exp_f32_e32 v92, v92
	v_exp_f32_e32 v93, v93
	v_add_f32_e32 v182, v90, v182
	v_add_f32_e32 v182, v91, v182
	v_cvt_pk_bf16_f32 v133, v90, v91
	v_mfma_f32_32x32x16_bf16 v[0:15], v[128:131], v[156:159], v[0:15]
	ds_read_b64_tr_b16 v[156:157], v252 offset:38400
	ds_read_b64_tr_b16 v[158:159], v252 offset:40448
	v_exp_f32_e32 v94, v94
	v_exp_f32_e32 v95, v95
	v_add_f32_e32 v182, v92, v182
	v_add_f32_e32 v182, v93, v182
	v_cvt_pk_bf16_f32 v134, v92, v93
	v_cvt_pk_bf16_f32 v135, v94, v95
	v_add_f32_e32 v182, v94, v182
	v_add_f32_e32 v182, v95, v182
	v_mfma_f32_32x32x16_bf16 v[112:127], v[192:195], v[172:175], v[112:127]
	v_mfma_f32_32x32x16_bf16 v[96:111], v[196:199], v[172:175], v[96:111]
	v_mfma_f32_32x32x16_bf16 v[112:127], v[200:203], v[168:171], v[112:127]
	v_mfma_f32_32x32x16_bf16 v[96:111], v[204:207], v[168:171], v[96:111]
	s_waitcnt lgkmcnt(4)
	v_mfma_f32_32x32x16_bf16 v[48:63], v[132:135], v[144:147], v[48:63]
	ds_read_b64_tr_b16 v[144:145], v252 offset:40960
	ds_read_b64_tr_b16 v[146:147], v252 offset:43008
	v_exp_f32_e32 v64, v64
	v_exp_f32_e32 v65, v65
	v_mfma_f32_32x32x16_bf16 v[32:47], v[132:135], v[148:151], v[32:47]
	ds_read_b64_tr_b16 v[148:149], v252 offset:41472
	ds_read_b64_tr_b16 v[150:151], v252 offset:43520
	v_exp_f32_e32 v66, v66
	v_exp_f32_e32 v67, v67
	v_add_f32_e32 v182, v64, v182
	v_add_f32_e32 v182, v65, v182
	v_cvt_pk_bf16_f32 v136, v64, v65
	s_waitcnt lgkmcnt(4)
	v_mfma_f32_32x32x16_bf16 v[16:31], v[132:135], v[152:155], v[16:31]
	ds_read_b64_tr_b16 v[152:153], v252 offset:41984
	ds_read_b64_tr_b16 v[154:155], v252 offset:44032
	v_exp_f32_e32 v68, v68
	v_exp_f32_e32 v69, v69
	v_add_f32_e32 v182, v66, v182
	v_add_f32_e32 v182, v67, v182
	v_cvt_pk_bf16_f32 v137, v66, v67
	v_mfma_f32_32x32x16_bf16 v[0:15], v[132:135], v[156:159], v[0:15]
	ds_read_b64_tr_b16 v[156:157], v252 offset:42496
	ds_read_b64_tr_b16 v[158:159], v252 offset:44544
	v_exp_f32_e32 v70, v70
	v_exp_f32_e32 v71, v71
	v_add_f32_e32 v182, v68, v182
	v_add_f32_e32 v182, v69, v182
	v_cvt_pk_bf16_f32 v138, v68, v69
	v_cvt_pk_bf16_f32 v139, v70, v71
	v_add_f32_e32 v182, v70, v182
	v_add_f32_e32 v182, v71, v182
	v_mfma_f32_32x32x16_bf16 v[112:127], v[208:211], v[164:167], v[112:127]
	v_mfma_f32_32x32x16_bf16 v[96:111], v[212:215], v[164:167], v[96:111]
	v_mfma_f32_32x32x16_bf16 v[112:127], v[216:219], v[160:163], v[112:127]
	v_mfma_f32_32x32x16_bf16 v[96:111], v[220:223], v[160:163], v[96:111]
	s_waitcnt lgkmcnt(4)
	v_mfma_f32_32x32x16_bf16 v[48:63], v[136:139], v[144:147], v[48:63]
	ds_read_b64_tr_b16 v[144:145], v252 offset:45056
	ds_read_b64_tr_b16 v[146:147], v252 offset:47104
	v_exp_f32_e32 v72, v72
	v_exp_f32_e32 v73, v73
	v_mfma_f32_32x32x16_bf16 v[32:47], v[136:139], v[148:151], v[32:47]
	ds_read_b64_tr_b16 v[148:149], v252 offset:45568
	ds_read_b64_tr_b16 v[150:151], v252 offset:47616
	v_exp_f32_e32 v74, v74
	v_exp_f32_e32 v75, v75
	v_add_f32_e32 v182, v72, v182
	v_add_f32_e32 v182, v73, v182
	v_cvt_pk_bf16_f32 v140, v72, v73
	s_waitcnt lgkmcnt(4)
	v_mfma_f32_32x32x16_bf16 v[16:31], v[136:139], v[152:155], v[16:31]
	ds_read_b64_tr_b16 v[152:153], v252 offset:46080
	ds_read_b64_tr_b16 v[154:155], v252 offset:48128
	v_exp_f32_e32 v76, v76
	v_exp_f32_e32 v77, v77
	v_add_f32_e32 v182, v74, v182
	v_add_f32_e32 v182, v75, v182
	v_cvt_pk_bf16_f32 v141, v74, v75
	v_mfma_f32_32x32x16_bf16 v[0:15], v[136:139], v[156:159], v[0:15]
	ds_read_b64_tr_b16 v[156:157], v252 offset:46592
	ds_read_b64_tr_b16 v[158:159], v252 offset:48640
	v_exp_f32_e32 v78, v78
	v_exp_f32_e32 v79, v79
	v_add_f32_e32 v182, v76, v182
	v_add_f32_e32 v182, v77, v182
	v_cvt_pk_bf16_f32 v142, v76, v77
	v_cvt_pk_bf16_f32 v143, v78, v79
	v_add_f32_e32 v182, v78, v182
	v_add_f32_e32 v182, v79, v182
	s_waitcnt lgkmcnt(4)
	v_mfma_f32_32x32x16_bf16 v[48:63], v[140:143], v[144:147], v[48:63]
	v_exp_f32_e32 v112, v112
	v_exp_f32_e32 v113, v113
	v_mfma_f32_32x32x16_bf16 v[32:47], v[140:143], v[148:151], v[32:47]
	v_exp_f32_e32 v114, v114
	v_exp_f32_e32 v115, v115
	v_add_f32_e32 v182, v112, v182
	v_add_f32_e32 v182, v113, v182
	v_cvt_pk_bf16_f32 v128, v112, v113
	s_waitcnt lgkmcnt(0)
	v_mfma_f32_32x32x16_bf16 v[16:31], v[140:143], v[152:155], v[16:31]
	v_exp_f32_e32 v116, v116
	v_exp_f32_e32 v117, v117
	v_add_f32_e32 v182, v114, v182
	v_add_f32_e32 v182, v115, v182
	v_cvt_pk_bf16_f32 v129, v114, v115
	v_mfma_f32_32x32x16_bf16 v[0:15], v[140:143], v[156:159], v[0:15]
	v_exp_f32_e32 v118, v118
	v_exp_f32_e32 v119, v119
	v_add_f32_e32 v182, v116, v182
	v_add_f32_e32 v182, v117, v182
	v_cvt_pk_bf16_f32 v130, v116, v117
	v_cvt_pk_bf16_f32 v131, v118, v119
	v_add_f32_e32 v182, v118, v182
	v_add_f32_e32 v182, v119, v182
	s_add_i32 s54, s54, 1
	s_cmp_ge_i32 s54, s62
	s_cbranch_scc1 .Lsym_last3
	s_waitcnt vmcnt(0)
	s_barrier
	ds_read_b128 v[192:195], v178 offset:0
	ds_read_b128 v[196:199], v178 offset:8192
	ds_read_b128 v[200:203], v179 offset:0
	ds_read_b128 v[204:207], v179 offset:8192
	ds_read_b128 v[208:211], v180 offset:0
	ds_read_b128 v[212:215], v180 offset:8192
	ds_read_b128 v[216:219], v181 offset:0
	ds_read_b128 v[220:223], v181 offset:8192
	s_add_i32 s53, s54, 2
	s_cmp_le_i32 s53, s62
	s_cbranch_scc0 .Lsym_nostage_s3
	s_add_i32 m0, s25, 0x4000
	s_add_u32 s60, s56, 0x70000
	s_addc_u32 s61, s57, 0
	global_load_lds_dwordx4 v176, s[56:57]
	s_add_i32 m0, s24, 0x4000
	s_nop 0
	global_load_lds_dwordx4 v188, s[56:57]
	s_add_i32 m0, s25, 0x6000
	s_add_u32 s56, s56, 0xe0000
	s_addc_u32 s57, s57, 0
	global_load_lds_dwordx4 v176, s[60:61]
	s_add_i32 m0, s24, 0x6000
	s_nop 0
	global_load_lds_dwordx4 v188, s[60:61]

; #define SBAR() __builtin_amdgcn_sched_barrier(0)
; #define PK4(P, BASE, OUT) do { u32x4 w = {cvtpk(P[BASE + 0], P[BASE + 1]), cvtpk(P[BASE + 2], P[BASE + 3]), cvtpk(P[BASE + 4], P[BASE + 5]), cvtpk(P[BASE + 6], P[BASE + 7])}; \
;     OUT = *reinterpret_cast<bf16x8*>(&w); } while (0)
; template <int KS> __device__ __forceinline__ void pv_ks(f32x16* o, int vb, bf16x8 pa) {
;     const s16x4 l0 = tr_read<v_rd_off(0, KS, 0)>(vb), h0 = tr_read<v_rd_off(0, KS, 1)>(vb), l1 = tr_read<v_rd_off(1, KS, 0)>(vb), h1 = tr_read<v_rd_off(1, KS, 1)>(vb);
;     const s16x4 l2 = tr_read<v_rd_off(2, KS, 0)>(vb), h2 = tr_read<v_rd_off(2, KS, 1)>(vb), l3 = tr_read<v_rd_off(3, KS, 0)>(vb), h3 = tr_read<v_rd_off(3, KS, 1)>(vb);
;     ...
;     asm volatile("s_waitcnt lgkmcnt(6)" ::: "memory"); SBAR();
;     o[0] = __builtin_amdgcn_mfma_f32_32x32x16_bf16(pa, PK(l0, h0), o[0], 0, 0, 0);
;     asm volatile("s_waitcnt lgkmcnt(4)" ::: "memory"); SBAR();
;     o[1] = __builtin_amdgcn_mfma_f32_32x32x16_bf16(pa, PK(l1, h1), o[1], 0, 0, 0);
;     asm volatile("s_waitcnt lgkmcnt(2)" ::: "memory"); SBAR();
;     o[2] = __builtin_amdgcn_mfma_f32_32x32x16_bf16(pa, PK(l2, h2), o[2], 0, 0, 0);
;     asm volatile("s_waitcnt lgkmcnt(0)" ::: "memory"); SBAR();
;     o[3] = __builtin_amdgcn_mfma_f32_32x32x16_bf16(pa, PK(l3, h3), o[3], 0, 0, 0);
;     ...
; }
; __device__ __forceinline__ void pv_d0(f32x16* o, int vb, bf16x8 pa0, bf16x8 pa1, bf16x8 pa2, bf16x8 pa3) {
;     __builtin_amdgcn_s_setprio(1);
;     pv_ks<0>(o, vb, pa0); pv_ks<1>(o, vb, pa1); pv_ks<2>(o, vb, pa2); pv_ks<3>(o, vb, pa3);
;     __builtin_amdgcn_s_setprio(0);
; }
; __device__ __forceinline__ void exp_half(f32x16& p) {
; #pragma unroll
;     for (int r = 0; r < 16; ++r) p[r] = __builtin_amdgcn_exp2f(p[r]);
; }
; __device__ __forceinline__ void pack_p(const f32x16& p0, const f32x16& p1, float& l_reg, bf16x8& pa0, bf16x8& pa1, bf16x8& pa2, bf16x8& pa3) {
;     float ps = 0;
; #pragma unroll
;     for (int r = 0; r < 16; ++r) ps += p0[r];
; #pragma unroll
;     for (int r = 0; r < 16; ++r) ps += p1[r];
;     l_reg += ps;
;     ...
;     PK4(p0, 0, pa0); PK4(p0, 8, pa1); PK4(p1, 0, pa2); PK4(p1, 8, pa3);
;     ...
; }
.Lsym_biasdone_s3:
	s_add_i32 s55, s55, 64
	v_add_f32_e32 v183, 0xc2800000, v183
	ds_read_b64_tr_b16 v[144:145], v252 offset:49152
	ds_read_b64_tr_b16 v[146:147], v252 offset:51200
	ds_read_b64_tr_b16 v[148:149], v252 offset:49664
	ds_read_b64_tr_b16 v[150:151], v252 offset:51712
	ds_read_b64_tr_b16 v[152:153], v252 offset:50176
	ds_read_b64_tr_b16 v[154:155], v252 offset:52224
	ds_read_b64_tr_b16 v[156:157], v252 offset:50688
	ds_read_b64_tr_b16 v[158:159], v252 offset:52736
	s_waitcnt lgkmcnt(4)
	v_mfma_f32_32x32x16_bf16 v[48:63], v[128:131], v[144:147], v[48:63]
	ds_read_b64_tr_b16 v[144:145], v252 offset:53248
	ds_read_b64_tr_b16 v[146:147], v252 offset:55296
	v_exp_f32_e32 v120, v120
	v_exp_f32_e32 v121, v121
	v_mfma_f32_32x32x16_bf16 v[32:47], v[128:131], v[148:151], v[32:47]
	ds_read_b64_tr_b16 v[148:149], v252 offset:53760
	ds_read_b64_tr_b16 v[150:151], v252 offset:55808
	v_exp_f32_e32 v122, v122
	v_exp_f32_e32 v123, v123
	v_add_f32_e32 v182, v120, v182
	v_add_f32_e32 v182, v121, v182
	v_cvt_pk_bf16_f32 v132, v120, v121
	s_waitcnt lgkmcnt(4)
	v_mfma_f32_32x32x16_bf16 v[16:31], v[128:131], v[152:155], v[16:31]
	ds_read_b64_tr_b16 v[152:153], v252 offset:54272
	ds_read_b64_tr_b16 v[154:155], v252 offset:56320
	v_exp_f32_e32 v124, v124
	v_exp_f32_e32 v125, v125
	v_add_f32_e32 v182, v122, v182
	v_add_f32_e32 v182, v123, v182
	v_cvt_pk_bf16_f32 v133, v122, v123
	v_mfma_f32_32x32x16_bf16 v[0:15], v[128:131], v[156:159], v[0:15]
	ds_read_b64_tr_b16 v[156:157], v252 offset:54784
	ds_read_b64_tr_b16 v[158:159], v252 offset:56832
	v_exp_f32_e32 v126, v126
	v_exp_f32_e32 v127, v127
	v_add_f32_e32 v182, v124, v182
	v_add_f32_e32 v182, v125, v182
	v_cvt_pk_bf16_f32 v134, v124, v125
	v_cvt_pk_bf16_f32 v135, v126, v127
	v_add_f32_e32 v182, v126, v182
	v_add_f32_e32 v182, v127, v182
	v_mfma_f32_32x32x16_bf16 v[80:95], v[192:195], v[172:175], v[80:95]
	v_mfma_f32_32x32x16_bf16 v[64:79], v[196:199], v[172:175], v[64:79]
	v_mfma_f32_32x32x16_bf16 v[80:95], v[200:203], v[168:171], v[80:95]
	v_mfma_f32_32x32x16_bf16 v[64:79], v[204:207], v[168:171], v[64:79]
	s_waitcnt lgkmcnt(4)
	v_mfma_f32_32x32x16_bf16 v[48:63], v[132:135], v[144:147], v[48:63]
	ds_read_b64_tr_b16 v[144:145], v252 offset:57344
	ds_read_b64_tr_b16 v[146:147], v252 offset:59392
	v_exp_f32_e32 v96, v96
	v_exp_f32_e32 v97, v97
	v_mfma_f32_32x32x16_bf16 v[32:47], v[132:135], v[148:151], v[32:47]
	ds_read_b64_tr_b16 v[148:149], v252 offset:57856
	ds_read_b64_tr_b16 v[150:151], v252 offset:59904
	v_exp_f32_e32 v98, v98
	v_exp_f32_e32 v99, v99
	v_add_f32_e32 v182, v96, v182
	v_add_f32_e32 v182, v97, v182
	v_cvt_pk_bf16_f32 v136, v96, v97
	s_waitcnt lgkmcnt(4)
	v_mfma_f32_32x32x16_bf16 v[16:31], v[132:135], v[152:155], v[16:31]
	ds_read_b64_tr_b16 v[152:153], v252 offset:58368
	ds_read_b64_tr_b16 v[154:155], v252 offset:60416
	v_exp_f32_e32 v100, v100
	v_exp_f32_e32 v101, v101
	v_add_f32_e32 v182, v98, v182
	v_add_f32_e32 v182, v99, v182
	v_cvt_pk_bf16_f32 v137, v98, v99
	v_mfma_f32_32x32x16_bf16 v[0:15], v[132:135], v[156:159], v[0:15]
	ds_read_b64_tr_b16 v[156:157], v252 offset:58880
	ds_read_b64_tr_b16 v[158:159], v252 offset:60928
	v_exp_f32_e32 v102, v102
	v_exp_f32_e32 v103, v103
	v_add_f32_e32 v182, v100, v182
	v_add_f32_e32 v182, v101, v182
	v_cvt_pk_bf16_f32 v138, v100, v101
	v_cvt_pk_bf16_f32 v139, v102, v103
	v_add_f32_e32 v182, v102, v182
	v_add_f32_e32 v182, v103, v182
	v_mfma_f32_32x32x16_bf16 v[80:95], v[208:211], v[164:167], v[80:95]
	v_mfma_f32_32x32x16_bf16 v[64:79], v[212:215], v[164:167], v[64:79]
	v_mfma_f32_32x32x16_bf16 v[80:95], v[216:219], v[160:163], v[80:95]
	v_mfma_f32_32x32x16_bf16 v[64:79], v[220:223], v[160:163], v[64:79]
	s_waitcnt lgkmcnt(4)
	v_mfma_f32_32x32x16_bf16 v[48:63], v[136:139], v[144:147], v[48:63]
	ds_read_b64_tr_b16 v[144:145], v252 offset:61440
	ds_read_b64_tr_b16 v[146:147], v252 offset:63488
	v_exp_f32_e32 v104, v104
	v_exp_f32_e32 v105, v105
	v_mfma_f32_32x32x16_bf16 v[32:47], v[136:139], v[148:151], v[32:47]
	ds_read_b64_tr_b16 v[148:149], v252 offset:61952
	ds_read_b64_tr_b16 v[150:151], v252 offset:64000
	v_exp_f32_e32 v106, v106
	v_exp_f32_e32 v107, v107
	v_add_f32_e32 v182, v104, v182
	v_add_f32_e32 v182, v105, v182
	v_cvt_pk_bf16_f32 v140, v104, v105
	s_waitcnt lgkmcnt(4)
	v_mfma_f32_32x32x16_bf16 v[16:31], v[136:139], v[152:155], v[16:31]
	ds_read_b64_tr_b16 v[152:153], v252 offset:62464
	ds_read_b64_tr_b16 v[154:155], v252 offset:64512
	v_exp_f32_e32 v108, v108
	v_exp_f32_e32 v109, v109
	v_add_f32_e32 v182, v106, v182
	v_add_f32_e32 v182, v107, v182
	v_cvt_pk_bf16_f32 v141, v106, v107
	v_mfma_f32_32x32x16_bf16 v[0:15], v[136:139], v[156:159], v[0:15]
	ds_read_b64_tr_b16 v[156:157], v252 offset:62976
	ds_read_b64_tr_b16 v[158:159], v252 offset:65024
	v_exp_f32_e32 v110, v110
	v_exp_f32_e32 v111, v111
	v_add_f32_e32 v182, v108, v182
	v_add_f32_e32 v182, v109, v182
	v_cvt_pk_bf16_f32 v142, v108, v109
	v_cvt_pk_bf16_f32 v143, v110, v111
	v_add_f32_e32 v182, v110, v182
	v_add_f32_e32 v182, v111, v182
	s_waitcnt lgkmcnt(4)
	v_mfma_f32_32x32x16_bf16 v[48:63], v[140:143], v[144:147], v[48:63]
	v_exp_f32_e32 v80, v80
	v_exp_f32_e32 v81, v81
	v_mfma_f32_32x32x16_bf16 v[32:47], v[140:143], v[148:151], v[32:47]
	v_exp_f32_e32 v82, v82
	v_exp_f32_e32 v83, v83
	v_add_f32_e32 v182, v80, v182
	v_add_f32_e32 v182, v81, v182
	v_cvt_pk_bf16_f32 v128, v80, v81
	s_waitcnt lgkmcnt(0)
	v_mfma_f32_32x32x16_bf16 v[16:31], v[140:143], v[152:155], v[16:31]
	v_exp_f32_e32 v84, v84
	v_exp_f32_e32 v85, v85
	v_add_f32_e32 v182, v82, v182
	v_add_f32_e32 v182, v83, v182
	v_cvt_pk_bf16_f32 v129, v82, v83
	v_mfma_f32_32x32x16_bf16 v[0:15], v[140:143], v[156:159], v[0:15]
	v_exp_f32_e32 v86, v86
	v_exp_f32_e32 v87, v87
	v_add_f32_e32 v182, v84, v182
	v_add_f32_e32 v182, v85, v182
	v_cvt_pk_bf16_f32 v130, v84, v85
	v_cvt_pk_bf16_f32 v131, v86, v87
	v_add_f32_e32 v182, v86, v182
	v_add_f32_e32 v182, v87, v182
	s_add_i32 s54, s54, 1
	s_branch .Lsym_loop
; #define SBAR() __builtin_amdgcn_sched_barrier(0)
; #define PK4(P, BASE, OUT) do { u32x4 w = {cvtpk(P[BASE + 0], P[BASE + 1]), cvtpk(P[BASE + 2], P[BASE + 3]), cvtpk(P[BASE + 4], P[BASE + 5]), cvtpk(P[BASE + 6], P[BASE + 7])}; \
;     OUT = *reinterpret_cast<bf16x8*>(&w); } while (0)
; template <int KS> __device__ __forceinline__ void pv_ks(f32x16* o, int vb, bf16x8 pa) {
;     const s16x4 l0 = tr_read<v_rd_off(0, KS, 0)>(vb), h0 = tr_read<v_rd_off(0, KS, 1)>(vb), l1 = tr_read<v_rd_off(1, KS, 0)>(vb), h1 = tr_read<v_rd_off(1, KS, 1)>(vb);
;     const s16x4 l2 = tr_read<v_rd_off(2, KS, 0)>(vb), h2 = tr_read<v_rd_off(2, KS, 1)>(vb), l3 = tr_read<v_rd_off(3, KS, 0)>(vb), h3 = tr_read<v_rd_off(3, KS, 1)>(vb);
;     ...
;     asm volatile("s_waitcnt lgkmcnt(6)" ::: "memory"); SBAR();
;     o[0] = __builtin_amdgcn_mfma_f32_32x32x16_bf16(pa, PK(l0, h0), o[0], 0, 0, 0);
;     asm volatile("s_waitcnt lgkmcnt(4)" ::: "memory"); SBAR();
;     o[1] = __builtin_amdgcn_mfma_f32_32x32x16_bf16(pa, PK(l1, h1), o[1], 0, 0, 0);
;     asm volatile("s_waitcnt lgkmcnt(2)" ::: "memory"); SBAR();
;     o[2] = __builtin_amdgcn_mfma_f32_32x32x16_bf16(pa, PK(l2, h2), o[2], 0, 0, 0);
;     asm volatile("s_waitcnt lgkmcnt(0)" ::: "memory"); SBAR();
;     o[3] = __builtin_amdgcn_mfma_f32_32x32x16_bf16(pa, PK(l3, h3), o[3], 0, 0, 0);
;     ...
; }
; __device__ __forceinline__ void pv_d0(f32x16* o, int vb, bf16x8 pa0, bf16x8 pa1, bf16x8 pa2, bf16x8 pa3) {
;     __builtin_amdgcn_s_setprio(1);
;     pv_ks<0>(o, vb, pa0); pv_ks<1>(o, vb, pa1); pv_ks<2>(o, vb, pa2); pv_ks<3>(o, vb, pa3);
;     __builtin_amdgcn_s_setprio(0);
; }
; __device__ __forceinline__ void exp_half(f32x16& p) {
; #pragma unroll
;     for (int r = 0; r < 16; ++r) p[r] = __builtin_amdgcn_exp2f(p[r]);
; }
; __device__ __forceinline__ void pack_p(const f32x16& p0, const f32x16& p1, float& l_reg, bf16x8& pa0, bf16x8& pa1, bf16x8& pa2, bf16x8& pa3) {
;     float ps = 0;
; #pragma unroll
;     for (int r = 0; r < 16; ++r) ps += p0[r];
; #pragma unroll
;     for (int r = 0; r < 16; ++r) ps += p1[r];
;     l_reg += ps;
;     ...
;     PK4(p0, 0, pa0); PK4(p0, 8, pa1); PK4(p1, 0, pa2); PK4(p1, 8, pa3);
;     ...
; }
.Lsym_last1:
	s_waitcnt vmcnt(0)
	s_barrier
	ds_read_b64_tr_b16 v[144:145], v252 offset:16384
	ds_read_b64_tr_b16 v[146:147], v252 offset:18432
	ds_read_b64_tr_b16 v[148:149], v252 offset:16896
	ds_read_b64_tr_b16 v[150:151], v252 offset:18944
	ds_read_b64_tr_b16 v[152:153], v252 offset:17408
	ds_read_b64_tr_b16 v[154:155], v252 offset:19456
	ds_read_b64_tr_b16 v[156:157], v252 offset:17920
	ds_read_b64_tr_b16 v[158:159], v252 offset:19968
	s_waitcnt lgkmcnt(4)
	v_mfma_f32_32x32x16_bf16 v[48:63], v[128:131], v[144:147], v[48:63]
	ds_read_b64_tr_b16 v[144:145], v252 offset:20480
	ds_read_b64_tr_b16 v[146:147], v252 offset:22528
	v_exp_f32_e32 v120, v120
	v_exp_f32_e32 v121, v121
	v_mfma_f32_32x32x16_bf16 v[32:47], v[128:131], v[148:151], v[32:47]
	ds_read_b64_tr_b16 v[148:149], v252 offset:20992
	ds_read_b64_tr_b16 v[150:151], v252 offset:23040
	v_exp_f32_e32 v122, v122
	v_exp_f32_e32 v123, v123
	v_add_f32_e32 v182, v120, v182
	v_add_f32_e32 v182, v121, v182
	v_cvt_pk_bf16_f32 v132, v120, v121
	s_waitcnt lgkmcnt(4)
	v_mfma_f32_32x32x16_bf16 v[16:31], v[128:131], v[152:155], v[16:31]
	ds_read_b64_tr_b16 v[152:153], v252 offset:21504
	ds_read_b64_tr_b16 v[154:155], v252 offset:23552
	v_exp_f32_e32 v124, v124
	v_exp_f32_e32 v125, v125
	v_add_f32_e32 v182, v122, v182
	v_add_f32_e32 v182, v123, v182
	v_cvt_pk_bf16_f32 v133, v122, v123
	v_mfma_f32_32x32x16_bf16 v[0:15], v[128:131], v[156:159], v[0:15]
	ds_read_b64_tr_b16 v[156:157], v252 offset:22016
	ds_read_b64_tr_b16 v[158:159], v252 offset:24064
	v_exp_f32_e32 v126, v126
	v_exp_f32_e32 v127, v127
	v_add_f32_e32 v182, v124, v182
	v_add_f32_e32 v182, v125, v182
	v_cvt_pk_bf16_f32 v134, v124, v125
	v_cvt_pk_bf16_f32 v135, v126, v127
	v_add_f32_e32 v182, v126, v182
	v_add_f32_e32 v182, v127, v182
	s_waitcnt lgkmcnt(4)
	v_mfma_f32_32x32x16_bf16 v[48:63], v[132:135], v[144:147], v[48:63]
	ds_read_b64_tr_b16 v[144:145], v252 offset:24576
	ds_read_b64_tr_b16 v[146:147], v252 offset:26624
	v_exp_f32_e32 v96, v96
	v_exp_f32_e32 v97, v97
	v_mfma_f32_32x32x16_bf16 v[32:47], v[132:135], v[148:151], v[32:47]
	ds_read_b64_tr_b16 v[148:149], v252 offset:25088
	ds_read_b64_tr_b16 v[150:151], v252 offset:27136
	v_exp_f32_e32 v98, v98
	v_exp_f32_e32 v99, v99
	v_add_f32_e32 v182, v96, v182
	v_add_f32_e32 v182, v97, v182
	v_cvt_pk_bf16_f32 v136, v96, v97
	s_waitcnt lgkmcnt(4)
	v_mfma_f32_32x32x16_bf16 v[16:31], v[132:135], v[152:155], v[16:31]
	ds_read_b64_tr_b16 v[152:153], v252 offset:25600
	ds_read_b64_tr_b16 v[154:155], v252 offset:27648
	v_exp_f32_e32 v100, v100
	v_exp_f32_e32 v101, v101
	v_add_f32_e32 v182, v98, v182
	v_add_f32_e32 v182, v99, v182
	v_cvt_pk_bf16_f32 v137, v98, v99
	v_mfma_f32_32x32x16_bf16 v[0:15], v[132:135], v[156:159], v[0:15]
	ds_read_b64_tr_b16 v[156:157], v252 offset:26112
	ds_read_b64_tr_b16 v[158:159], v252 offset:28160
	v_exp_f32_e32 v102, v102
	v_exp_f32_e32 v103, v103
	v_add_f32_e32 v182, v100, v182
	v_add_f32_e32 v182, v101, v182
	v_cvt_pk_bf16_f32 v138, v100, v101
	v_cvt_pk_bf16_f32 v139, v102, v103
	v_add_f32_e32 v182, v102, v182
	v_add_f32_e32 v182, v103, v182
	s_waitcnt lgkmcnt(4)
	v_mfma_f32_32x32x16_bf16 v[48:63], v[136:139], v[144:147], v[48:63]
	ds_read_b64_tr_b16 v[144:145], v252 offset:28672
	ds_read_b64_tr_b16 v[146:147], v252 offset:30720
	v_exp_f32_e32 v104, v104
	v_exp_f32_e32 v105, v105
	v_mfma_f32_32x32x16_bf16 v[32:47], v[136:139], v[148:151], v[32:47]
	ds_read_b64_tr_b16 v[148:149], v252 offset:29184
	ds_read_b64_tr_b16 v[150:151], v252 offset:31232
	v_exp_f32_e32 v106, v106
	v_exp_f32_e32 v107, v107
	v_add_f32_e32 v182, v104, v182
	v_add_f32_e32 v182, v105, v182
	v_cvt_pk_bf16_f32 v140, v104, v105
	s_waitcnt lgkmcnt(4)
	v_mfma_f32_32x32x16_bf16 v[16:31], v[136:139], v[152:155], v[16:31]
	ds_read_b64_tr_b16 v[152:153], v252 offset:29696
	ds_read_b64_tr_b16 v[154:155], v252 offset:31744
	v_exp_f32_e32 v108, v108
	v_exp_f32_e32 v109, v109
	v_add_f32_e32 v182, v106, v182
	v_add_f32_e32 v182, v107, v182
	v_cvt_pk_bf16_f32 v141, v106, v107
	v_mfma_f32_32x32x16_bf16 v[0:15], v[136:139], v[156:159], v[0:15]
	ds_read_b64_tr_b16 v[156:157], v252 offset:30208
	ds_read_b64_tr_b16 v[158:159], v252 offset:32256
	v_exp_f32_e32 v110, v110
	v_exp_f32_e32 v111, v111
	v_add_f32_e32 v182, v108, v182
	v_add_f32_e32 v182, v109, v182
	v_cvt_pk_bf16_f32 v142, v108, v109
	v_cvt_pk_bf16_f32 v143, v110, v111
	v_add_f32_e32 v182, v110, v182
	v_add_f32_e32 v182, v111, v182
	s_waitcnt lgkmcnt(4)
	v_mfma_f32_32x32x16_bf16 v[48:63], v[140:143], v[144:147], v[48:63]
	v_mfma_f32_32x32x16_bf16 v[32:47], v[140:143], v[148:151], v[32:47]
	s_waitcnt lgkmcnt(0)
	v_mfma_f32_32x32x16_bf16 v[16:31], v[140:143], v[152:155], v[16:31]
	v_mfma_f32_32x32x16_bf16 v[0:15], v[140:143], v[156:159], v[0:15]
	s_branch .Lsym_done
; #define SBAR() __builtin_amdgcn_sched_barrier(0)
; #define PK4(P, BASE, OUT) do { u32x4 w = {cvtpk(P[BASE + 0], P[BASE + 1]), cvtpk(P[BASE + 2], P[BASE + 3]), cvtpk(P[BASE + 4], P[BASE + 5]), cvtpk(P[BASE + 6], P[BASE + 7])}; \
;     OUT = *reinterpret_cast<bf16x8*>(&w); } while (0)
; template <int KS> __device__ __forceinline__ void pv_ks(f32x16* o, int vb, bf16x8 pa) {
;     const s16x4 l0 = tr_read<v_rd_off(0, KS, 0)>(vb), h0 = tr_read<v_rd_off(0, KS, 1)>(vb), l1 = tr_read<v_rd_off(1, KS, 0)>(vb), h1 = tr_read<v_rd_off(1, KS, 1)>(vb);
;     const s16x4 l2 = tr_read<v_rd_off(2, KS, 0)>(vb), h2 = tr_read<v_rd_off(2, KS, 1)>(vb), l3 = tr_read<v_rd_off(3, KS, 0)>(vb), h3 = tr_read<v_rd_off(3, KS, 1)>(vb);
;     ...
;     asm volatile("s_waitcnt lgkmcnt(6)" ::: "memory"); SBAR();
;     o[0] = __builtin_amdgcn_mfma_f32_32x32x16_bf16(pa, PK(l0, h0), o[0], 0, 0, 0);
;     asm volatile("s_waitcnt lgkmcnt(4)" ::: "memory"); SBAR();
;     o[1] = __builtin_amdgcn_mfma_f32_32x32x16_bf16(pa, PK(l1, h1), o[1], 0, 0, 0);
;     asm volatile("s_waitcnt lgkmcnt(2)" ::: "memory"); SBAR();
;     o[2] = __builtin_amdgcn_mfma_f32_32x32x16_bf16(pa, PK(l2, h2), o[2], 0, 0, 0);
;     asm volatile("s_waitcnt lgkmcnt(0)" ::: "memory"); SBAR();
;     o[3] = __builtin_amdgcn_mfma_f32_32x32x16_bf16(pa, PK(l3, h3), o[3], 0, 0, 0);
;     ...
; }
; __device__ __forceinline__ void pv_d0(f32x16* o, int vb, bf16x8 pa0, bf16x8 pa1, bf16x8 pa2, bf16x8 pa3) {
;     __builtin_amdgcn_s_setprio(1);
;     pv_ks<0>(o, vb, pa0); pv_ks<1>(o, vb, pa1); pv_ks<2>(o, vb, pa2); pv_ks<3>(o, vb, pa3);
;     __builtin_amdgcn_s_setprio(0);
; }
; __device__ __forceinline__ void exp_half(f32x16& p) {
; #pragma unroll
;     for (int r = 0; r < 16; ++r) p[r] = __builtin_amdgcn_exp2f(p[r]);
; }
; __device__ __forceinline__ void pack_p(const f32x16& p0, const f32x16& p1, float& l_reg, bf16x8& pa0, bf16x8& pa1, bf16x8& pa2, bf16x8& pa3) {
;     float ps = 0;
; #pragma unroll
;     for (int r = 0; r < 16; ++r) ps += p0[r];
; #pragma unroll
;     for (int r = 0; r < 16; ++r) ps += p1[r];
;     l_reg += ps;
;     ...
;     PK4(p0, 0, pa0); PK4(p0, 8, pa1); PK4(p1, 0, pa2); PK4(p1, 8, pa3);
;     ...
; }
.Lsym_last3:
	s_waitcnt vmcnt(0)
	s_barrier
	ds_read_b64_tr_b16 v[144:145], v252 offset:49152
	ds_read_b64_tr_b16 v[146:147], v252 offset:51200
	ds_read_b64_tr_b16 v[148:149], v252 offset:49664
	ds_read_b64_tr_b16 v[150:151], v252 offset:51712
	ds_read_b64_tr_b16 v[152:153], v252 offset:50176
	ds_read_b64_tr_b16 v[154:155], v252 offset:52224
	ds_read_b64_tr_b16 v[156:157], v252 offset:50688
	ds_read_b64_tr_b16 v[158:159], v252 offset:52736
	s_waitcnt lgkmcnt(4)
	v_mfma_f32_32x32x16_bf16 v[48:63], v[128:131], v[144:147], v[48:63]
	ds_read_b64_tr_b16 v[144:145], v252 offset:53248
	ds_read_b64_tr_b16 v[146:147], v252 offset:55296
	v_exp_f32_e32 v120, v120
	v_exp_f32_e32 v121, v121
	v_mfma_f32_32x32x16_bf16 v[32:47], v[128:131], v[148:151], v[32:47]
	ds_read_b64_tr_b16 v[148:149], v252 offset:53760
	ds_read_b64_tr_b16 v[150:151], v252 offset:55808
	v_exp_f32_e32 v122, v122
	v_exp_f32_e32 v123, v123
	v_add_f32_e32 v182, v120, v182
	v_add_f32_e32 v182, v121, v182
	v_cvt_pk_bf16_f32 v132, v120, v121
	s_waitcnt lgkmcnt(4)
	v_mfma_f32_32x32x16_bf16 v[16:31], v[128:131], v[152:155], v[16:31]
	ds_read_b64_tr_b16 v[152:153], v252 offset:54272
	ds_read_b64_tr_b16 v[154:155], v252 offset:56320
	v_exp_f32_e32 v124, v124
	v_exp_f32_e32 v125, v125
	v_add_f32_e32 v182, v122, v182
	v_add_f32_e32 v182, v123, v182
	v_cvt_pk_bf16_f32 v133, v122, v123
	v_mfma_f32_32x32x16_bf16 v[0:15], v[128:131], v[156:159], v[0:15]
	ds_read_b64_tr_b16 v[156:157], v252 offset:54784
	ds_read_b64_tr_b16 v[158:159], v252 offset:56832
	v_exp_f32_e32 v126, v126
	v_exp_f32_e32 v127, v127
	v_add_f32_e32 v182, v124, v182
	v_add_f32_e32 v182, v125, v182
	v_cvt_pk_bf16_f32 v134, v124, v125
	v_cvt_pk_bf16_f32 v135, v126, v127
	v_add_f32_e32 v182, v126, v182
	v_add_f32_e32 v182, v127, v182
	s_waitcnt lgkmcnt(4)
	v_mfma_f32_32x32x16_bf16 v[48:63], v[132:135], v[144:147], v[48:63]
	ds_read_b64_tr_b16 v[144:145], v252 offset:57344
	ds_read_b64_tr_b16 v[146:147], v252 offset:59392
	v_exp_f32_e32 v96, v96
	v_exp_f32_e32 v97, v97
	v_mfma_f32_32x32x16_bf16 v[32:47], v[132:135], v[148:151], v[32:47]
	ds_read_b64_tr_b16 v[148:149], v252 offset:57856
	ds_read_b64_tr_b16 v[150:151], v252 offset:59904
	v_exp_f32_e32 v98, v98
	v_exp_f32_e32 v99, v99
	v_add_f32_e32 v182, v96, v182
	v_add_f32_e32 v182, v97, v182
	v_cvt_pk_bf16_f32 v136, v96, v97
	s_waitcnt lgkmcnt(4)
	v_mfma_f32_32x32x16_bf16 v[16:31], v[132:135], v[152:155], v[16:31]
	ds_read_b64_tr_b16 v[152:153], v252 offset:58368
	ds_read_b64_tr_b16 v[154:155], v252 offset:60416
	v_exp_f32_e32 v100, v100
	v_exp_f32_e32 v101, v101
	v_add_f32_e32 v182, v98, v182
	v_add_f32_e32 v182, v99, v182
	v_cvt_pk_bf16_f32 v137, v98, v99
	v_mfma_f32_32x32x16_bf16 v[0:15], v[132:135], v[156:159], v[0:15]
	ds_read_b64_tr_b16 v[156:157], v252 offset:58880
	ds_read_b64_tr_b16 v[158:159], v252 offset:60928
	v_exp_f32_e32 v102, v102
	v_exp_f32_e32 v103, v103
	v_add_f32_e32 v182, v100, v182
	v_add_f32_e32 v182, v101, v182
	v_cvt_pk_bf16_f32 v138, v100, v101
	v_cvt_pk_bf16_f32 v139, v102, v103
	v_add_f32_e32 v182, v102, v182
	v_add_f32_e32 v182, v103, v182
	s_waitcnt lgkmcnt(4)
	v_mfma_f32_32x32x16_bf16 v[48:63], v[136:139], v[144:147], v[48:63]
	ds_read_b64_tr_b16 v[144:145], v252 offset:61440
	ds_read_b64_tr_b16 v[146:147], v252 offset:63488
	v_exp_f32_e32 v104, v104
	v_exp_f32_e32 v105, v105
	v_mfma_f32_32x32x16_bf16 v[32:47], v[136:139], v[148:151], v[32:47]
	ds_read_b64_tr_b16 v[148:149], v252 offset:61952
	ds_read_b64_tr_b16 v[150:151], v252 offset:64000
	v_exp_f32_e32 v106, v106
	v_exp_f32_e32 v107, v107
	v_add_f32_e32 v182, v104, v182
	v_add_f32_e32 v182, v105, v182
	v_cvt_pk_bf16_f32 v140, v104, v105
	s_waitcnt lgkmcnt(4)
	v_mfma_f32_32x32x16_bf16 v[16:31], v[136:139], v[152:155], v[16:31]
	ds_read_b64_tr_b16 v[152:153], v252 offset:62464
	ds_read_b64_tr_b16 v[154:155], v252 offset:64512
	v_exp_f32_e32 v108, v108
	v_exp_f32_e32 v109, v109
	v_add_f32_e32 v182, v106, v182
	v_add_f32_e32 v182, v107, v182
	v_cvt_pk_bf16_f32 v141, v106, v107
	v_mfma_f32_32x32x16_bf16 v[0:15], v[136:139], v[156:159], v[0:15]
	ds_read_b64_tr_b16 v[156:157], v252 offset:62976
	ds_read_b64_tr_b16 v[158:159], v252 offset:65024
	v_exp_f32_e32 v110, v110
	v_exp_f32_e32 v111, v111
	v_add_f32_e32 v182, v108, v182
	v_add_f32_e32 v182, v109, v182
	v_cvt_pk_bf16_f32 v142, v108, v109
	v_cvt_pk_bf16_f32 v143, v110, v111
	v_add_f32_e32 v182, v110, v182
	v_add_f32_e32 v182, v111, v182
	s_waitcnt lgkmcnt(4)
	v_mfma_f32_32x32x16_bf16 v[48:63], v[140:143], v[144:147], v[48:63]
	v_mfma_f32_32x32x16_bf16 v[32:47], v[140:143], v[148:151], v[32:47]
	s_waitcnt lgkmcnt(0)
	v_mfma_f32_32x32x16_bf16 v[16:31], v[140:143], v[152:155], v[16:31]
	v_mfma_f32_32x32x16_bf16 v[0:15], v[140:143], v[156:159], v[0:15]
